# v68 + layer-1 w_kv transposes deferred to P4 head and w_out1 transposes to P6 head (odd XCDs); P3 idle CUs keep only w_in_b
# speedup vs baseline: 1.0029x; 1.0018x over previous
.LBB0_454:
	s_mov_b32 s100, 0
	s_movk_i32 s101, 0x1000
	s_lshr_b32 s0, s95, 30
	s_add_i32 s0, s94, s0
	s_ashr_i32 s12, s0, 2
	s_sub_i32 s0, s94, s12
	s_add_u32 s22, s92, 0x4500000
	s_addc_u32 s23, s93, 0
	s_add_u32 s40, s92, 0x1400000
	s_addc_u32 s41, s93, 0
	s_cmp_lt_i32 s2, s0
	s_cbranch_scc1 .LBB0_469
	v_mov_b32_e32 v0, v210
	s_sub_i32 s0, s2, s0
	s_lshl_b32 s0, s0, 3
	v_readfirstlane_b32 s1, v0
	s_ashr_i32 s13, s1, 6
	s_add_i32 s33, s13, s0
	s_cmp_ge_i32 s33, s101
	s_cbranch_scc1 .LBB0_469
.Lp3t_setup:
	v_readlane_b32 s48, v233, 39
	s_lshl_b32 s42, s12, 3
	v_readlane_b32 s60, v233, 51
	v_readlane_b32 s49, v233, 40
	v_readlane_b32 s50, v233, 41
	v_readlane_b32 s51, v233, 42
	v_readlane_b32 s52, v233, 43
	v_readlane_b32 s53, v233, 44
	v_readlane_b32 s54, v233, 45
	v_readlane_b32 s55, v233, 46
	v_readlane_b32 s56, v233, 47
	v_readlane_b32 s57, v233, 48
	v_readlane_b32 s58, v233, 49
	v_readlane_b32 s59, v233, 50
	v_readlane_b32 s61, v233, 52
	v_readlane_b32 s62, v233, 53
	v_readlane_b32 s63, v233, 54
	s_add_u32 s0, s60, 0x1000000
	s_addc_u32 s1, s61, 0
	v_readlane_b32 s48, v233, 21
	v_readlane_b32 s62, v233, 35
	v_readlane_b32 s63, v233, 36
	s_cmp_lg_u64 s[62:63], 0
	s_cselect_b64 s[4:5], -1, 0
	s_lshl_b32 s13, s13, 14
	v_bfe_u32 v20, v0, 5, 1
	v_and_b32_e32 v2, 31, v0
	v_readlane_b32 s49, v233, 22
	v_readlane_b32 s50, v233, 23
	v_readlane_b32 s51, v233, 24
	v_readlane_b32 s52, v233, 25
	v_readlane_b32 s53, v233, 26
	v_readlane_b32 s54, v233, 27
	v_readlane_b32 s55, v233, 28
	v_readlane_b32 s56, v233, 29
	v_readlane_b32 s57, v233, 30
	v_readlane_b32 s58, v233, 31
	v_readlane_b32 s59, v233, 32
	v_readlane_b32 s60, v233, 33
	v_readlane_b32 s61, v233, 34
	s_add_i32 s13, s13, 0
	v_and_b32_e32 v1, 7, v0
	v_lshlrev_b32_e32 v3, 2, v2
	v_mul_u32_u24_e32 v4, 0x84, v20
	v_bfe_u32 v22, v0, 3, 3
	s_mov_b64 s[14:15], s[62:63]
	v_mov_b32_e32 v9, 0
	v_add3_u32 v21, s13, v3, v4
	v_mul_u32_u24_e32 v0, 0x420, v1
	v_lshlrev_b32_e32 v3, 2, v22
	v_readlane_b32 s48, v233, 2
	v_lshlrev_b32_e32 v8, 4, v1
	v_add3_u32 v23, s13, v0, v3
	v_lshlrev_b32_e32 v0, 5, v1
	v_mov_b32_e32 v1, v9
	v_readlane_b32 s52, v233, 6
	v_readlane_b32 s53, v233, 7
	v_lshl_add_u64 v[12:13], s[14:15], 0, v[0:1]
	v_readlane_b32 s49, v233, 3
	v_readlane_b32 s50, v233, 4
	v_readlane_b32 s51, v233, 5
	v_lshl_add_u64 v[0:1], s[52:53], 0, v[0:1]
	s_mov_b64 s[14:15], 0x2000
	v_lshl_add_u64 v[10:11], s[22:23], 0, v[8:9]
	v_or_b32_e32 v24, 8, v22
	v_or_b32_e32 v25, 16, v22
	v_or_b32_e32 v26, 24, v22
	v_lshl_add_u64 v[14:15], v[0:1], 0, s[14:15]
	v_lshl_add_u64 v[16:17], s[40:41], 0, v[8:9]
	s_lshl_b32 s43, s33, 5
	s_lshl_b32 s44, s12, 8
	s_mov_b32 s45, 0x18000
	s_mov_b32 s48, 0x30000
	s_mov_b32 s49, 0x48000
	s_mov_b32 s50, 0x60000
	s_mov_b32 s51, 0x78000
	s_mov_b32 s52, 0x90000
	s_mov_b32 s53, 0xa8000
	v_lshlrev_b32_e32 v18, 2, v2
	v_add_u32_e32 v27, 0x400, v21
	v_add_u32_e32 v28, 0x800, v21
	v_add_u32_e32 v29, 0xc00, v21
	v_add_u32_e32 v30, 0x1000, v21
	v_add_u32_e32 v31, 0x1400, v21
	v_add_u32_e32 v32, 0x1800, v21
	v_add_u32_e32 v33, 0x1c00, v21
	s_mov_b32 s13, 0
	s_mov_b64 s[26:27], s[70:71]
	v_readlane_b32 s54, v233, 8
	v_readlane_b32 s55, v233, 9
	v_readlane_b32 s56, v233, 10
	v_readlane_b32 s57, v233, 11
	v_readlane_b32 s58, v233, 12
	v_readlane_b32 s59, v233, 13
	v_readlane_b32 s60, v233, 14
	v_readlane_b32 s61, v233, 15
	v_readlane_b32 s62, v233, 16
	v_readlane_b32 s63, v233, 17
	s_branch .LBB0_458
.LBB0_457:
	s_add_i32 s33, s33, s42
	s_add_i32 s43, s43, s44
	s_cmp_lt_i32 s33, s101
	s_cbranch_scc0 .LBB0_469

.LBB0_469:
	s_cmp_eq_u32 s100, 4
	s_cbranch_scc1 .Ldf_ret_p4
	s_cmp_eq_u32 s100, 5
	s_cbranch_scc1 .Ldf_ret_p6
	s_waitcnt vmcnt(0)
	s_barrier
	s_mov_b64 s[0:1], exec
	v_readlane_b32 s4, v233, 0
	v_readlane_b32 s5, v233, 1
	s_and_b64 s[4:5], s[0:1], s[4:5]
	s_mov_b64 exec, s[4:5]
	s_cbranch_execz .LBB0_521
	s_add_i32 s4, 0, 0x23fc0
	v_mov_b32_e32 v0, s4
	s_waitcnt vmcnt(0) expcnt(0) lgkmcnt(0)
	ds_read_b32 v2, v0
	s_add_i32 s4, 0, 0x23fc4
	v_mov_b32_e32 v0, s4
	ds_read_b32 v0, v0
	s_waitcnt lgkmcnt(1)
	v_cmp_ne_u32_e32 vcc, 0, v2
	s_cbranch_vccnz .LBB0_485
	s_mov_b32 s24, 1
	v_mov_b32_e32 v16, 0
	s_branch .LBB0_473

.LBB0_627:
	s_or_b64 exec, exec, s[0:1]
	s_bitcmp1_b32 s2, 0
	s_cbranch_scc0 .Ldf_skip_p4
	v_writelane_b32 v234, s0, 0
	v_writelane_b32 v234, s1, 1
	v_writelane_b32 v234, s2, 2
	v_writelane_b32 v234, s3, 3
	v_writelane_b32 v234, s4, 4
	v_writelane_b32 v234, s5, 5
	v_writelane_b32 v234, s6, 6
	v_writelane_b32 v234, s7, 7
	v_writelane_b32 v234, s8, 8
	v_writelane_b32 v234, s9, 9
	v_writelane_b32 v234, s10, 10
	v_writelane_b32 v234, s11, 11
	v_writelane_b32 v234, s12, 12
	v_writelane_b32 v234, s13, 13
	v_writelane_b32 v234, s14, 14
	v_writelane_b32 v234, s15, 15
	v_writelane_b32 v234, s16, 16
	v_writelane_b32 v234, s17, 17
	v_writelane_b32 v234, s18, 18
	v_writelane_b32 v234, s19, 19
	v_writelane_b32 v234, s20, 20
	v_writelane_b32 v234, s21, 21
	v_writelane_b32 v234, s22, 22
	v_writelane_b32 v234, s23, 23
	v_writelane_b32 v234, s24, 24
	v_writelane_b32 v234, s25, 25
	v_writelane_b32 v234, s26, 26
	v_writelane_b32 v234, s27, 27
	v_writelane_b32 v234, s28, 28
	v_writelane_b32 v234, s29, 29
	v_writelane_b32 v234, s30, 30
	v_writelane_b32 v234, s31, 31
	v_writelane_b32 v234, s32, 32
	v_writelane_b32 v234, s33, 33
	v_writelane_b32 v234, s34, 34
	v_writelane_b32 v234, s35, 35
	v_writelane_b32 v234, s36, 36
	v_writelane_b32 v234, s37, 37
	v_writelane_b32 v234, s38, 38
	v_writelane_b32 v234, s39, 39
	v_writelane_b32 v234, s40, 40
	v_writelane_b32 v234, s41, 41
	v_writelane_b32 v234, s42, 42
	v_writelane_b32 v234, s43, 43
	v_writelane_b32 v234, s44, 44
	v_writelane_b32 v234, s45, 45
	v_writelane_b32 v234, s46, 46
	v_writelane_b32 v234, s47, 47
	v_writelane_b32 v234, s48, 48
	v_writelane_b32 v234, s49, 49
	v_writelane_b32 v234, s50, 50
	v_writelane_b32 v234, s51, 51
	v_writelane_b32 v234, s52, 52
	v_writelane_b32 v234, s53, 53
	v_writelane_b32 v234, s54, 54
	v_writelane_b32 v234, s55, 55
	v_writelane_b32 v234, s56, 56
	v_writelane_b32 v234, s57, 57
	v_writelane_b32 v234, s58, 58
	v_writelane_b32 v234, s59, 59
	v_writelane_b32 v234, s60, 60
	v_writelane_b32 v234, s61, 61
	v_writelane_b32 v234, s62, 62
	v_writelane_b32 v234, s63, 63
	v_writelane_b32 v235, s64, 0
	v_writelane_b32 v235, s65, 1
	v_writelane_b32 v235, s66, 2
	v_writelane_b32 v235, s67, 3
	v_writelane_b32 v235, s68, 4
	v_writelane_b32 v235, s69, 5
	v_writelane_b32 v235, s70, 6
	v_writelane_b32 v235, s71, 7
	v_writelane_b32 v235, s72, 8
	v_writelane_b32 v235, s73, 9
	v_writelane_b32 v235, s74, 10
	v_writelane_b32 v235, s75, 11
	v_writelane_b32 v235, s76, 12
	v_writelane_b32 v235, s77, 13
	v_writelane_b32 v235, s78, 14
	v_writelane_b32 v235, s79, 15
	v_writelane_b32 v235, s80, 16
	v_writelane_b32 v235, s81, 17
	v_writelane_b32 v235, s82, 18
	v_writelane_b32 v235, s83, 19
	v_writelane_b32 v235, s84, 20
	v_writelane_b32 v235, s85, 21
	v_writelane_b32 v235, s86, 22
	v_writelane_b32 v235, s87, 23
	v_writelane_b32 v235, s88, 24
	v_writelane_b32 v235, s89, 25
	v_writelane_b32 v235, s90, 26
	v_writelane_b32 v235, s91, 27
	v_writelane_b32 v235, s92, 28
	v_writelane_b32 v235, s93, 29
	v_writelane_b32 v235, s94, 30
	v_writelane_b32 v235, s95, 31
	v_writelane_b32 v235, s96, 32
	v_writelane_b32 v235, s97, 33
	v_writelane_b32 v235, vcc_lo, 34
	v_writelane_b32 v235, vcc_hi, 35
	v_readlane_b32 s70, v233, 45
	v_readlane_b32 s71, v233, 46
	s_add_u32 s22, s92, 0x4500000
	s_addc_u32 s23, s93, 0
	s_add_u32 s40, s92, 0x1400000
	s_addc_u32 s41, s93, 0
	v_mov_b32_e32 v0, v210
	s_nop 0
	v_readfirstlane_b32 s1, v0
	s_nop 3
	s_ashr_i32 s13, s1, 6
	s_lshr_b32 s0, s2, 1
	s_lshl_b32 s0, s0, 3
	s_add_i32 s33, s13, s0
	s_addk_i32 s33, 0x1000
	s_movk_i32 s12, 0x80
	s_movk_i32 s101, 0x1c00
	s_mov_b32 s100, 4
	s_branch .Lp3t_setup

.Ldf_skip_p4:
	s_cmpk_lt_i32 s2, 0x200
	v_mov_b32_e32 v11, v210
	s_waitcnt lgkmcnt(0)
	s_barrier
	s_cselect_b64 s[0:1], -1, 0
	s_cmpk_gt_i32 s2, 0x1ff
	s_nop 0
	v_readfirstlane_b32 s24, v11
	s_cbranch_scc1 .LBB0_629
	s_lshr_b32 s4, s3, 29
	s_add_i32 s4, s2, s4
	s_and_b32 s5, s4, -8
	s_sub_i32 s5, s2, s5
	s_lshl_b32 s13, s5, 6
	s_ashr_i32 s4, s4, 3
	s_mul_i32 s12, s5, 0x41
	s_cmp_lt_i32 s5, 0
	s_cselect_b32 s5, s12, s13
	s_add_i32 s4, s5, s4
	s_ashr_i32 s5, s4, 31
	s_lshr_b32 s5, s5, 27
	s_add_i32 s5, s4, s5
	s_ashr_i32 s12, s5, 5
	s_andn2_b32 s5, s5, 31
	s_sub_i32 s4, s4, s5
	s_bfe_i32 s5, s4, 0x80000
	s_bfe_u32 s5, s5, 0x2000d
	s_add_i32 s5, s4, s5
	s_bfe_i32 s13, s5, 0x80000
	s_and_b32 s5, s5, 0xfc
	s_sub_i32 s4, s4, s5
	s_lshl_b32 s12, s12, 2
	s_sext_i32_i16 s13, s13
	s_sext_i32_i8 s4, s4
	s_add_i32 s56, s12, s4
	s_ashr_i32 s14, s13, 2

.LBB0_783:
	s_or_b64 exec, exec, s[0:1]
	s_bitcmp1_b32 s2, 0
	s_cbranch_scc0 .Ldf_skip_p6
	v_writelane_b32 v234, s0, 0
	v_writelane_b32 v234, s1, 1
	v_writelane_b32 v234, s2, 2
	v_writelane_b32 v234, s3, 3
	v_writelane_b32 v234, s4, 4
	v_writelane_b32 v234, s5, 5
	v_writelane_b32 v234, s6, 6
	v_writelane_b32 v234, s7, 7
	v_writelane_b32 v234, s8, 8
	v_writelane_b32 v234, s9, 9
	v_writelane_b32 v234, s10, 10
	v_writelane_b32 v234, s11, 11
	v_writelane_b32 v234, s12, 12
	v_writelane_b32 v234, s13, 13
	v_writelane_b32 v234, s14, 14
	v_writelane_b32 v234, s15, 15
	v_writelane_b32 v234, s16, 16
	v_writelane_b32 v234, s17, 17
	v_writelane_b32 v234, s18, 18
	v_writelane_b32 v234, s19, 19
	v_writelane_b32 v234, s20, 20
	v_writelane_b32 v234, s21, 21
	v_writelane_b32 v234, s22, 22
	v_writelane_b32 v234, s23, 23
	v_writelane_b32 v234, s24, 24
	v_writelane_b32 v234, s25, 25
	v_writelane_b32 v234, s26, 26
	v_writelane_b32 v234, s27, 27
	v_writelane_b32 v234, s28, 28
	v_writelane_b32 v234, s29, 29
	v_writelane_b32 v234, s30, 30
	v_writelane_b32 v234, s31, 31
	v_writelane_b32 v234, s32, 32
	v_writelane_b32 v234, s33, 33
	v_writelane_b32 v234, s34, 34
	v_writelane_b32 v234, s35, 35
	v_writelane_b32 v234, s36, 36
	v_writelane_b32 v234, s37, 37
	v_writelane_b32 v234, s38, 38
	v_writelane_b32 v234, s39, 39
	v_writelane_b32 v234, s40, 40
	v_writelane_b32 v234, s41, 41
	v_writelane_b32 v234, s42, 42
	v_writelane_b32 v234, s43, 43
	v_writelane_b32 v234, s44, 44
	v_writelane_b32 v234, s45, 45
	v_writelane_b32 v234, s46, 46
	v_writelane_b32 v234, s47, 47
	v_writelane_b32 v234, s48, 48
	v_writelane_b32 v234, s49, 49
	v_writelane_b32 v234, s50, 50
	v_writelane_b32 v234, s51, 51
	v_writelane_b32 v234, s52, 52
	v_writelane_b32 v234, s53, 53
	v_writelane_b32 v234, s54, 54
	v_writelane_b32 v234, s55, 55
	v_writelane_b32 v234, s56, 56
	v_writelane_b32 v234, s57, 57
	v_writelane_b32 v234, s58, 58
	v_writelane_b32 v234, s59, 59
	v_writelane_b32 v234, s60, 60
	v_writelane_b32 v234, s61, 61
	v_writelane_b32 v234, s62, 62
	v_writelane_b32 v234, s63, 63
	v_writelane_b32 v235, s64, 0
	v_writelane_b32 v235, s65, 1
	v_writelane_b32 v235, s66, 2
	v_writelane_b32 v235, s67, 3
	v_writelane_b32 v235, s68, 4
	v_writelane_b32 v235, s69, 5
	v_writelane_b32 v235, s70, 6
	v_writelane_b32 v235, s71, 7
	v_writelane_b32 v235, s72, 8
	v_writelane_b32 v235, s73, 9
	v_writelane_b32 v235, s74, 10
	v_writelane_b32 v235, s75, 11
	v_writelane_b32 v235, s76, 12
	v_writelane_b32 v235, s77, 13
	v_writelane_b32 v235, s78, 14
	v_writelane_b32 v235, s79, 15
	v_writelane_b32 v235, s80, 16
	v_writelane_b32 v235, s81, 17
	v_writelane_b32 v235, s82, 18
	v_writelane_b32 v235, s83, 19
	v_writelane_b32 v235, s84, 20
	v_writelane_b32 v235, s85, 21
	v_writelane_b32 v235, s86, 22
	v_writelane_b32 v235, s87, 23
	v_writelane_b32 v235, s88, 24
	v_writelane_b32 v235, s89, 25
	v_writelane_b32 v235, s90, 26
	v_writelane_b32 v235, s91, 27
	v_writelane_b32 v235, s92, 28
	v_writelane_b32 v235, s93, 29
	v_writelane_b32 v235, s94, 30
	v_writelane_b32 v235, s95, 31
	v_writelane_b32 v235, s96, 32
	v_writelane_b32 v235, s97, 33
	v_writelane_b32 v235, vcc_lo, 34
	v_writelane_b32 v235, vcc_hi, 35
	v_readlane_b32 s70, v233, 45
	v_readlane_b32 s71, v233, 46
	s_add_u32 s22, s92, 0x4500000
	s_addc_u32 s23, s93, 0
	s_add_u32 s40, s92, 0x1400000
	s_addc_u32 s41, s93, 0
	v_mov_b32_e32 v0, v210
	s_nop 0
	v_readfirstlane_b32 s1, v0
	s_nop 3
	s_ashr_i32 s13, s1, 6
	s_lshr_b32 s0, s2, 1
	s_lshl_b32 s0, s0, 3
	s_add_i32 s33, s13, s0
	s_addk_i32 s33, 0x1c00
	s_movk_i32 s12, 0x80
	s_movk_i32 s101, 0x2400
	s_mov_b32 s100, 5
	s_branch .Lp3t_setup

.Ldf_skip_p6:
	s_waitcnt vmcnt(7) lgkmcnt(0)
	v_mov_b32_e32 v0, v210
	s_barrier
	v_lshl_add_u32 v236, s2, 9, v210
	v_mov_b32_e32 v237, 0
	v_lshlrev_b64 v[236:237], 7, v[236:237]
	s_add_u32 s98, s92, 0x1400000
	s_addc_u32 s99, s93, 0
	v_lshl_add_u64 v[236:237], s[98:99], 0, v[236:237]
	global_load_dword v234, v[236:237], off
	s_mov_b64 s[100:101], 0x1000000
	v_lshl_add_u64 v[236:237], v[236:237], 0, s[100:101]
	global_load_dword v234, v[236:237], off
	s_cmpk_lt_i32 s2, 0x60
	s_cselect_b64 s[0:1], -1, 0
	v_readfirstlane_b32 s4, v0
	s_cmp_lt_u32 s4, 64
	s_cselect_b64 s[4:5], -1, 0
	s_and_b64 s[0:1], s[4:5], s[0:1]
	s_and_b64 vcc, exec, s[0:1]
	s_cbranch_vccz .LBB0_786
	v_mbcnt_hi_u32_b32 v1, -1, v211
	s_waitcnt vmcnt(6)
	v_and_b32_e32 v7, 64, v1
	v_add_u32_e32 v2, -1, v1
	v_cmp_lt_i32_e32 vcc, v2, v7
	v_add_u32_e32 v3, -2, v1
	v_add_u32_e32 v4, -4, v1
	v_cndmask_b32_e32 v2, v2, v1, vcc
	v_cmp_lt_i32_e32 vcc, v3, v7
	v_add_u32_e32 v5, -8, v1
	v_add_u32_e32 v6, -16, v1
	v_cndmask_b32_e32 v3, v3, v1, vcc
	v_cmp_lt_i32_e32 vcc, v4, v7
	s_waitcnt vmcnt(5)
	v_subrev_u32_e32 v8, 32, v1
	s_lshl_b64 s[0:1], s[2:3], 13
	v_cndmask_b32_e32 v4, v4, v1, vcc
	v_cmp_lt_i32_e32 vcc, v5, v7
	v_and_b32_e32 v0, 63, v0
	s_add_u32 s0, s92, s0
	v_cndmask_b32_e32 v5, v5, v1, vcc
	v_cmp_lt_i32_e32 vcc, v6, v7
	v_cmp_gt_u32_e64 s[42:43], 32, v0
	v_cmp_gt_u32_e64 s[44:45], 16, v0
	v_cndmask_b32_e32 v6, v6, v1, vcc
	v_cmp_lt_i32_e32 vcc, v8, v7
	v_cmp_gt_u32_e64 s[46:47], 8, v0
	v_cmp_gt_u32_e64 s[48:49], 4, v0
	v_cndmask_b32_e32 v1, v8, v1, vcc
	v_cmp_gt_u32_e64 s[50:51], 2, v0
	v_cmp_eq_u32_e64 s[52:53], 0, v0
	v_lshlrev_b32_e32 v7, 2, v1
	v_lshlrev_b32_e32 v0, 7, v0
	v_mov_b32_e32 v1, 0
	s_addc_u32 s1, s93, s1
	v_lshl_add_u64 v[0:1], s[0:1], 0, v[0:1]
	s_mov_b64 s[0:1], 0x120000
	v_lshlrev_b32_e32 v2, 2, v2
	v_lshlrev_b32_e32 v3, 2, v3
	v_lshlrev_b32_e32 v4, 2, v4
	v_lshlrev_b32_e32 v5, 2, v5
	v_lshlrev_b32_e32 v6, 2, v6
	v_lshl_add_u64 v[0:1], v[0:1], 0, s[0:1]
	s_lshl_b64 s[0:1], s[94:95], 13
	s_mov_b32 s4, s2
	s_mov_b32 s5, 0xfff31000
